# defer lr-tile LDS write until all item loads in flight (gla_local_item); drop initial cooperative grid.sync
# baseline (speedup 1.0000x reference)
; #define LAS __attribute__((address_space(3)))
; __device__ __forceinline__ unsigned xb_add(unsigned* p, unsigned v) { return __hip_atomic_fetch_add(p, v, __ATOMIC_RELAXED, __HIP_MEMORY_SCOPE_AGENT); }
; __device__ __forceinline__ unsigned xb_xcc_id() { return (unsigned)__builtin_amdgcn_s_getreg((3 << 11) | 20) & 0xFu; }
; __device__ __forceinline__ void phase_prep(const Params& p, LAS unsigned char* lds) {
;     ...
;     for (int i = blockIdx.x * NTHREADS + tid; i < 4 * T; i += gridDim.x * NTHREADS) sumsq[T + i] = 0ull;
; __global__ void __launch_bounds__(NTHREADS) fwd_megakernel(Params p) {
;     ...
;     XcdBarrier xb; xb.bar = bar; xb.x = xb_xcc_id(); xb.st = (volatile LAS unsigned*)(lds + 131072 + 16);
;     if (threadIdx.x == 0) { xb.st[0] = 0u; xb.st[1] = 0u; (void)xb_add(&bar[XB_XCNT(xb.x)], 1u); }
;     __syncthreads();
;     grid.sync();
.LBB0_3:
	s_or_b64 exec, exec, s[4:5]
	v_lshrrev_b32_e32 v1, 20, v0
	v_lshrrev_b32_e32 v0, 10, v0
	v_or_b32_e32 v0, v0, v1
	v_and_or_b32 v0, v0, s2, v200
	v_cmp_eq_u32_e32 vcc, 0, v0
	s_waitcnt lgkmcnt(0)
	s_barrier
	s_load_dwordx16 s[60:75], s[0:1], 0x0
	v_mov_b32_e32 v82, v200
	s_barrier
	s_waitcnt lgkmcnt(0)
	s_add_u32 s80, s58, 0x2d78c000
	v_lshl_add_u32 v64, s84, 9, v82
	s_mov_b32 s0, 0x10800
	s_addc_u32 s81, s59, 0
	v_cmp_gt_i32_e32 vcc, s0, v64
	s_and_saveexec_b64 s[0:1], vcc
	s_cbranch_execz .LBB0_16
	v_mov_b32_e32 v0, 0
	s_lshl_b32 s2, s3, 9
	s_mov_b64 s[4:5], 0
	v_mov_b32_e32 v1, v0
	s_mov_b32 s6, 0x107ff
	v_mov_b32_e32 v2, v64

; #define LAS __attribute__((address_space(3)))
; __device__ __forceinline__ void gla_gates(const Params& p, int l, int h, int tok0, int d, int tg, LAS float* gsum, float (&b)[16], float& blast) {
;     LAS float* lrs = gsum + 25088;
;     {
;         const int t2 = threadIdx.x;
;         if (t2 < 256) *(LAS f32x4*)(lrs + t2 * 4) = *(const f32x4*)((const float*)(p.ws + WS_ZLR) + (size_t)tok0 * 16 + t2 * 4);
;     }
;     const float* wg = p.w_gate_up + (size_t)l * 16 * 512 + h * 128 + d;
;     float w[16];
; #pragma unroll
;     for (int r = 0; r < 16; ++r) w[r] = wg[r * 512];
;     const float bg = p.b_gate[l * 512 + h * 128 + d];
;     __syncthreads();
; __device__ __forceinline__ void gla_local_item(const Params& p, int l, int c, int h, LAS unsigned char* lds) {
;     ...
;     const u16* kp = (const u16*)(ws + WS_ZK) + (size_t)(tok0 + tg * 16) * 512 + h * 128 + d;
;     u16 kraw[16];
; #pragma unroll
;     for (int i = 0; i < 16; ++i) kraw[i] = kp[i * 512];
;     const u16* vt = (const u16*)(ws + WS_ZVT) + (size_t)(h * 256 + w * 32 + fr) * T + tok0 + fq * 8;
;     bf16x8 bv[2][2];
; #pragma unroll
;     for (int kk = 0; kk < 2; ++kk)
; #pragma unroll
;         for (int n = 0; n < 2; ++n) bv[kk][n] = *(const bf16x8*)(vt + (size_t)(n * 16) * T + kk * 32);
.LBB0_503:
	v_mov_b32_e32 v30, v200
	s_and_b32 s1, s14, 0xffffffc
	v_ashrrev_i32_e32 v31, 7, v30
	v_add_lshl_u32 v18, v31, s1, 4
	v_ashrrev_i32_e32 v19, 31, v18
	v_and_b32_e32 v29, 0x7f, v30
	v_lshlrev_b64 v[2:3], 10, v[18:19]
	v_lshl_add_u64 v[2:3], s[40:41], 0, v[2:3]
	v_lshlrev_b32_e32 v0, 1, v29
	v_lshl_add_u64 v[2:3], v[2:3], 0, v[0:1]
	v_add_co_u32_e32 v4, vcc, s4, v2
	v_ashrrev_i32_e32 v0, 1, v30
	s_nop 0
	v_addc_co_u32_e32 v5, vcc, 0, v3, vcc
	v_add_co_u32_e32 v6, vcc, s92, v2
	v_and_b32_e32 v28, 0xffffffe0, v0
	s_nop 0
	v_addc_co_u32_e32 v7, vcc, 0, v3, vcc
	s_mov_b32 s0, s31
	v_add_co_u32_e32 v8, vcc, s5, v2
	v_and_b32_e32 v26, 15, v30
	v_add_u32_e32 v0, s29, v28
	s_and_b32 s18, s6, 0xffffffc0
	global_load_ushort v34, v[6:7], off offset:2048
	global_load_ushort v32, v[6:7], off offset:3072
	v_addc_co_u32_e32 v9, vcc, 0, v3, vcc
	global_load_ushort v46, v[2:3], off
	global_load_ushort v45, v[2:3], off offset:1024
	global_load_ushort v44, v[2:3], off offset:2048
	global_load_ushort v43, v[2:3], off offset:3072
	global_load_ushort v40, v[4:5], off offset:1024
	global_load_ushort v39, v[4:5], off offset:2048
	global_load_ushort v38, v[4:5], off offset:3072
	global_load_ushort v33, v[8:9], off
	v_or_b32_e32 v0, v0, v26
	v_mov_b64_e32 v[2:3], s[26:27]
	v_bfe_u32 v27, v30, 4, 2
	v_mad_i64_i32 v[2:3], s[10:11], v0, s96, v[2:3]
	s_ashr_i32 s19, s18, 31
	v_lshl_add_u64 v[2:3], s[18:19], 1, v[2:3]
	v_lshlrev_b32_e32 v0, 4, v27
	v_lshl_add_u64 v[2:3], v[2:3], 0, v[0:1]
	global_load_ushort v37, v[8:9], off offset:1024
	global_load_ushort v36, v[8:9], off offset:2048
	global_load_ushort v35, v[8:9], off offset:3072
	global_load_dwordx4 v[10:13], v[2:3], off
	v_add_co_u32_e32 v8, vcc, 0x84000, v2
	s_nop 1
	v_addc_co_u32_e32 v9, vcc, 0, v3, vcc
	global_load_dwordx4 v[14:17], v[8:9], off
	s_nop 0
	global_load_dwordx4 v[2:5], v[2:3], off offset:64
	s_nop 0
	global_load_ushort v47, v[6:7], off offset:-4096
	global_load_ushort v42, v[6:7], off
	global_load_ushort v41, v[6:7], off offset:1024
	s_nop 0
	global_load_dwordx4 v[6:9], v[8:9], off offset:64
	s_and_saveexec_b64 s[20:21], s[36:37]
	s_cbranch_execz .LBB0_505
	s_lshl_b64 s[10:11], s[18:19], 6
	v_lshl_add_u64 v[66:67], v[138:139], 0, s[10:11]
	global_load_dwordx4 v[66:69], v[66:67], off
.LBB0_505:
	s_or_b64 exec, exec, s[20:21]
	s_ashr_i32 s1, s0, 31
	s_lshl_b64 s[10:11], s[0:1], 15
	s_add_u32 s10, s76, s10
	v_lshlrev_b64 v[20:21], 9, v[18:19]
	s_addc_u32 s11, s25, s11
	v_lshlrev_b32_e32 v18, 2, v29
	v_mov_b32_e32 v19, v1
	v_lshl_add_u64 v[60:61], s[10:11], 0, v[18:19]
	v_add_co_u32_e32 v22, vcc, s4, v60
	global_load_dword v54, v18, s[10:11]
	global_load_dword v57, v18, s[10:11] offset:2048
	v_addc_co_u32_e32 v23, vcc, 0, v61, vcc
	v_add_co_u32_e32 v48, vcc, s92, v60
	s_movk_i32 s1, 0x4000
	s_nop 0
	v_addc_co_u32_e32 v49, vcc, 0, v61, vcc
	global_load_dword v58, v[48:49], off offset:-4096
	global_load_dword v59, v[22:23], off offset:2048
	global_load_dword v25, v[48:49], off
	s_nop 0
	global_load_dword v48, v[48:49], off offset:2048
	v_add_co_u32_e32 v22, vcc, s5, v60
	s_lshl_b32 s0, s0, 9
	s_nop 0
	v_addc_co_u32_e32 v23, vcc, 0, v61, vcc
	v_add_co_u32_e32 v52, vcc, s1, v60
	s_movk_i32 s1, 0x5000
	s_nop 0
	v_addc_co_u32_e32 v53, vcc, 0, v61, vcc
	global_load_dword v55, v[52:53], off offset:-4096
	global_load_dword v56, v[22:23], off offset:2048
	global_load_dword v50, v[52:53], off
	global_load_dword v51, v[52:53], off offset:2048
	v_add_co_u32_e32 v22, vcc, s1, v60
	s_movk_i32 s1, 0x6000
	s_nop 0
	v_addc_co_u32_e32 v23, vcc, 0, v61, vcc
	v_add_co_u32_e32 v62, vcc, s1, v60
	s_movk_i32 s1, 0x7000
	s_nop 0
	v_addc_co_u32_e32 v63, vcc, 0, v61, vcc
	v_add_co_u32_e32 v60, vcc, s1, v60
	s_or_b32 s0, s0, s28
	s_nop 0
	v_addc_co_u32_e32 v61, vcc, 0, v61, vcc
	global_load_dword v52, v[62:63], off offset:-4096
	global_load_dword v53, v[22:23], off offset:2048
	global_load_dword v19, v[62:63], off
	s_nop 0
	global_load_dword v22, v[62:63], off offset:2048
	global_load_dword v24, v[60:61], off
	global_load_dword v23, v[60:61], off offset:2048
	v_or_b32_e32 v60, s0, v29
	v_ashrrev_i32_e32 v61, 31, v60
	v_lshl_add_u64 v[60:61], v[60:61], 2, s[70:71]
	global_load_dword v61, v[60:61], off
	v_lshl_add_u32 v49, v31, 10, 0
	v_add_u32_e32 v60, 0x18800, v49
	s_waitcnt vmcnt(0)
	s_and_saveexec_b64 s[20:21], s[36:37]
	ds_write_b128 v201, v[66:69]
	s_or_b64 exec, exec, s[20:21]
	s_waitcnt vmcnt(0) lgkmcnt(0)
	s_barrier
; #define LAS __attribute__((address_space(3)))
; __device__ __forceinline__ void gla_gates(const Params& p, int l, int h, int tok0, int d, int tg, LAS float* gsum, float (&b)[16], float& blast) {
;     ...
;     for (int i = 0; i < 16; ++i) {
;         float x = bg;
; #pragma unroll
;         for (int r4 = 0; r4 < 4; ++r4) { const f32x4 a = *(const LAS f32x4*)(lr + i * 16 + r4 * 4);
;             x += a[0] * w[r4 * 4] + a[1] * w[r4 * 4 + 1] + a[2] * w[r4 * 4 + 2] + a[3] * w[r4 * 4 + 3]; }
;         const float ls = fminf(x, 0.f) - __logf(1.f + __expf(-fabsf(x)));
;         run += ls * (1.f / 16.f); b[i] = run;
;     }
	ds_read_b128 v[62:65], v60
	ds_read_b128 v[66:69], v60 offset:16
	ds_read_b128 v[70:73], v60 offset:32
	ds_read_b128 v[74:77], v60 offset:48
	v_lshl_add_u64 v[20:21], v[20:21], 1, s[78:79]
	s_waitcnt lgkmcnt(3)
	v_mul_f32_e32 v49, v57, v63
	v_fmac_f32_e32 v49, v54, v62
	v_fmac_f32_e32 v49, v58, v64
	v_fmac_f32_e32 v49, v59, v65
	s_waitcnt lgkmcnt(2)
	v_mul_f32_e32 v62, v48, v67
	v_fmac_f32_e32 v62, v25, v66
	v_fmac_f32_e32 v62, v55, v68
	v_fmac_f32_e32 v62, v56, v69
	v_add_f32_e32 v49, v61, v49
	v_add_f32_e32 v49, v49, v62
	s_waitcnt lgkmcnt(1)
	v_mul_f32_e32 v62, v51, v71
	v_fmac_f32_e32 v62, v50, v70
	v_fmac_f32_e32 v62, v52, v72
	v_fmac_f32_e32 v62, v53, v73
	v_add_f32_e32 v49, v49, v62
	s_waitcnt lgkmcnt(0)
	v_mul_f32_e32 v62, v22, v75
	v_fmac_f32_e32 v62, v19, v74
	v_fmac_f32_e32 v62, v24, v76
	v_fmac_f32_e32 v62, v23, v77
	v_add_f32_e32 v49, v49, v62
	v_min_f32_e32 v62, 0, v49
	v_mul_f32_e64 v49, |v49|, s8
	v_exp_f32_e32 v49, v49
	s_nop 0
	v_add_f32_e32 v49, 1.0, v49
	v_cmp_gt_f32_e32 vcc, s89, v49
	s_nop 1
	v_cndmask_b32_e64 v63, 0, 32, vcc
	v_ldexp_f32 v49, v49, v63
	v_log_f32_e32 v49, v49
	s_nop 0
	v_mul_f32_e32 v63, 0x3f317217, v49
	v_fma_f32 v63, v49, s9, -v63
	v_fmac_f32_e32 v63, 0x3377d1cf, v49
	v_fmac_f32_e32 v63, 0x3f317217, v49
	v_cmp_lt_f32_e64 s[0:1], |v49|, s88
	s_nop 1
	v_cndmask_b32_e64 v49, v49, v63, s[0:1]
	v_cndmask_b32_e32 v63, 0, v206, vcc
	v_sub_f32_e32 v49, v49, v63
	v_sub_f32_e32 v49, v62, v49
	ds_read_b128 v[62:65], v60 offset:64
	s_mov_b32 s0, 0x3d800000
	v_fma_f32 v49, v49, s0, 0
	s_waitcnt lgkmcnt(0)
	v_mul_f32_e32 v63, v57, v63
	v_fmac_f32_e32 v63, v54, v62
	v_fmac_f32_e32 v63, v58, v64
	v_fmac_f32_e32 v63, v59, v65
	v_add_f32_e32 v66, v61, v63
	ds_read_b128 v[62:65], v60 offset:80
	s_waitcnt lgkmcnt(0)
	v_mul_f32_e32 v63, v48, v63
	v_fmac_f32_e32 v63, v25, v62
	v_fmac_f32_e32 v63, v55, v64
	v_fmac_f32_e32 v63, v56, v65
	v_add_f32_e32 v66, v66, v63
	ds_read_b128 v[62:65], v60 offset:96
	s_waitcnt lgkmcnt(0)
	v_mul_f32_e32 v63, v51, v63
	v_fmac_f32_e32 v63, v50, v62
	v_fmac_f32_e32 v63, v52, v64
	v_fmac_f32_e32 v63, v53, v65
	v_add_f32_e32 v66, v66, v63
	ds_read_b128 v[62:65], v60 offset:112
	s_waitcnt lgkmcnt(0)
	v_mul_f32_e32 v63, v22, v63
	v_fmac_f32_e32 v63, v19, v62
	v_fmac_f32_e32 v63, v24, v64
	v_fmac_f32_e32 v63, v23, v65
	v_add_f32_e32 v62, v66, v63
	v_min_f32_e32 v63, 0, v62
	v_mul_f32_e64 v62, |v62|, s8
	v_exp_f32_e32 v62, v62
	s_nop 0
	v_add_f32_e32 v62, 1.0, v62
	v_cmp_gt_f32_e32 vcc, s89, v62
	s_nop 1
	v_cndmask_b32_e64 v64, 0, 32, vcc
	v_ldexp_f32 v62, v62, v64
	v_log_f32_e32 v62, v62
	s_nop 0
	v_mul_f32_e32 v64, 0x3f317217, v62
	v_fma_f32 v64, v62, s9, -v64
	v_fmac_f32_e32 v64, 0x3377d1cf, v62
	v_fmac_f32_e32 v64, 0x3f317217, v62
	v_cmp_lt_f32_e64 s[0:1], |v62|, s88
	s_nop 1
	v_cndmask_b32_e64 v62, v62, v64, s[0:1]
	v_cndmask_b32_e32 v64, 0, v206, vcc
	v_sub_f32_e32 v62, v62, v64
	ds_read_b128 v[64:67], v60 offset:128
	v_sub_f32_e32 v62, v63, v62
	v_fmamk_f32 v62, v62, 0x3d800000, v49
	s_waitcnt lgkmcnt(0)
	v_mul_f32_e32 v63, v57, v65
	v_fmac_f32_e32 v63, v54, v64
	v_fmac_f32_e32 v63, v58, v66
	v_fmac_f32_e32 v63, v59, v67
	ds_read_b128 v[64:67], v60 offset:144
	v_add_f32_e32 v63, v61, v63
	s_waitcnt lgkmcnt(0)
	v_mul_f32_e32 v65, v48, v65
	v_fmac_f32_e32 v65, v25, v64
	v_fmac_f32_e32 v65, v55, v66
	v_fmac_f32_e32 v65, v56, v67
	v_add_f32_e32 v63, v63, v65
	ds_read_b128 v[64:67], v60 offset:160
	s_waitcnt lgkmcnt(0)
	v_mul_f32_e32 v65, v51, v65
	v_fmac_f32_e32 v65, v50, v64
	v_fmac_f32_e32 v65, v52, v66
	v_fmac_f32_e32 v65, v53, v67
	v_add_f32_e32 v63, v63, v65
	ds_read_b128 v[64:67], v60 offset:176
	s_waitcnt lgkmcnt(0)
	v_mul_f32_e32 v65, v22, v65
	v_fmac_f32_e32 v65, v19, v64
	v_fmac_f32_e32 v65, v24, v66
	v_fmac_f32_e32 v65, v23, v67
	v_add_f32_e32 v63, v63, v65
	v_min_f32_e32 v64, 0, v63
	v_mul_f32_e64 v63, |v63|, s8
	v_exp_f32_e32 v63, v63
	s_nop 0
	v_add_f32_e32 v63, 1.0, v63
	v_cmp_gt_f32_e32 vcc, s89, v63
	s_nop 1
	v_cndmask_b32_e64 v65, 0, 32, vcc
	v_ldexp_f32 v63, v63, v65
	v_log_f32_e32 v63, v63
	s_nop 0
	v_mul_f32_e32 v65, 0x3f317217, v63
	v_fma_f32 v65, v63, s9, -v65
	v_fmac_f32_e32 v65, 0x3377d1cf, v63
	v_fmac_f32_e32 v65, 0x3f317217, v63
	v_cmp_lt_f32_e64 s[0:1], |v63|, s88
	s_nop 1
	v_cndmask_b32_e64 v63, v63, v65, s[0:1]
	v_cndmask_b32_e32 v65, 0, v206, vcc
	v_sub_f32_e32 v63, v63, v65
	v_sub_f32_e32 v63, v64, v63
	ds_read_b128 v[64:67], v60 offset:192
	v_fmamk_f32 v63, v63, 0x3d800000, v62
	s_waitcnt lgkmcnt(0)
	v_mul_f32_e32 v65, v57, v65
	v_fmac_f32_e32 v65, v54, v64
	v_fmac_f32_e32 v65, v58, v66
	v_fmac_f32_e32 v65, v59, v67
	v_add_f32_e32 v68, v61, v65
	ds_read_b128 v[64:67], v60 offset:208
	s_waitcnt lgkmcnt(0)
	v_mul_f32_e32 v65, v48, v65
	v_fmac_f32_e32 v65, v25, v64
	v_fmac_f32_e32 v65, v55, v66
	v_fmac_f32_e32 v65, v56, v67
	v_add_f32_e32 v68, v68, v65
	ds_read_b128 v[64:67], v60 offset:224
	s_waitcnt lgkmcnt(0)
	v_mul_f32_e32 v65, v51, v65
	v_fmac_f32_e32 v65, v50, v64
	v_fmac_f32_e32 v65, v52, v66
	v_fmac_f32_e32 v65, v53, v67
	v_add_f32_e32 v68, v68, v65
	ds_read_b128 v[64:67], v60 offset:240
	s_waitcnt lgkmcnt(0)
	v_mul_f32_e32 v65, v22, v65
	v_fmac_f32_e32 v65, v19, v64
	v_fmac_f32_e32 v65, v24, v66
	v_fmac_f32_e32 v65, v23, v67
	v_add_f32_e32 v64, v68, v65
	v_min_f32_e32 v65, 0, v64
	v_mul_f32_e64 v64, |v64|, s8
	v_exp_f32_e32 v64, v64
	s_nop 0
	v_add_f32_e32 v64, 1.0, v64
	v_cmp_gt_f32_e32 vcc, s89, v64
	s_nop 1
	v_cndmask_b32_e64 v66, 0, 32, vcc
	v_ldexp_f32 v64, v64, v66
	v_log_f32_e32 v64, v64
	s_nop 0
	v_mul_f32_e32 v66, 0x3f317217, v64
	v_fma_f32 v66, v64, s9, -v66
	v_fmac_f32_e32 v66, 0x3377d1cf, v64
	v_fmac_f32_e32 v66, 0x3f317217, v64
	v_cmp_lt_f32_e64 s[0:1], |v64|, s88
	s_nop 1
	v_cndmask_b32_e64 v64, v64, v66, s[0:1]
	v_cndmask_b32_e32 v66, 0, v206, vcc
	v_sub_f32_e32 v64, v64, v66
	ds_read_b128 v[66:69], v60 offset:256
	v_sub_f32_e32 v64, v65, v64
	v_fmamk_f32 v64, v64, 0x3d800000, v63
	s_waitcnt lgkmcnt(0)
; #define LAS __attribute__((address_space(3)))
; __device__ __forceinline__ void gla_gates(const Params& p, int l, int h, int tok0, int d, int tg, LAS float* gsum, float (&b)[16], float& blast) {
;     ...
;     for (int i = 0; i < 16; ++i) {
;         float x = bg;
; #pragma unroll
;         for (int r4 = 0; r4 < 4; ++r4) { const f32x4 a = *(const LAS f32x4*)(lr + i * 16 + r4 * 4);
;             x += a[0] * w[r4 * 4] + a[1] * w[r4 * 4 + 1] + a[2] * w[r4 * 4 + 2] + a[3] * w[r4 * 4 + 3]; }
;         const float ls = fminf(x, 0.f) - __logf(1.f + __expf(-fabsf(x)));
;         run += ls * (1.f / 16.f); b[i] = run;
;     }
	v_mul_f32_e32 v65, v57, v67
	v_fmac_f32_e32 v65, v54, v66
	v_fmac_f32_e32 v65, v58, v68
	v_fmac_f32_e32 v65, v59, v69
	ds_read_b128 v[66:69], v60 offset:272
	v_add_f32_e32 v65, v61, v65
	s_waitcnt lgkmcnt(0)
	v_mul_f32_e32 v67, v48, v67
	v_fmac_f32_e32 v67, v25, v66
	v_fmac_f32_e32 v67, v55, v68
	v_fmac_f32_e32 v67, v56, v69
	v_add_f32_e32 v65, v65, v67
	ds_read_b128 v[66:69], v60 offset:288
	s_waitcnt lgkmcnt(0)
	v_mul_f32_e32 v67, v51, v67
	v_fmac_f32_e32 v67, v50, v66
	v_fmac_f32_e32 v67, v52, v68
	v_fmac_f32_e32 v67, v53, v69
	v_add_f32_e32 v65, v65, v67
	ds_read_b128 v[66:69], v60 offset:304
	s_waitcnt lgkmcnt(0)
	v_mul_f32_e32 v67, v22, v67
	v_fmac_f32_e32 v67, v19, v66
	v_fmac_f32_e32 v67, v24, v68
	v_fmac_f32_e32 v67, v23, v69
	v_add_f32_e32 v65, v65, v67
	v_min_f32_e32 v66, 0, v65
	v_mul_f32_e64 v65, |v65|, s8
	v_exp_f32_e32 v65, v65
	s_nop 0
	v_add_f32_e32 v65, 1.0, v65
	v_cmp_gt_f32_e32 vcc, s89, v65
	s_nop 1
	v_cndmask_b32_e64 v67, 0, 32, vcc
	v_ldexp_f32 v65, v65, v67
	v_log_f32_e32 v65, v65
	s_nop 0
	v_mul_f32_e32 v67, 0x3f317217, v65
	v_fma_f32 v67, v65, s9, -v67
	v_fmac_f32_e32 v67, 0x3377d1cf, v65
	v_fmac_f32_e32 v67, 0x3f317217, v65
	v_cmp_lt_f32_e64 s[0:1], |v65|, s88
	s_nop 1
	v_cndmask_b32_e64 v65, v65, v67, s[0:1]
	v_cndmask_b32_e32 v67, 0, v206, vcc
	v_sub_f32_e32 v65, v65, v67
	v_sub_f32_e32 v65, v66, v65
	ds_read_b128 v[66:69], v60 offset:320
	v_fmamk_f32 v65, v65, 0x3d800000, v64
	s_waitcnt lgkmcnt(0)
	v_mul_f32_e32 v67, v57, v67
	v_fmac_f32_e32 v67, v54, v66
	v_fmac_f32_e32 v67, v58, v68
	v_fmac_f32_e32 v67, v59, v69
	v_add_f32_e32 v70, v61, v67
	ds_read_b128 v[66:69], v60 offset:336
	s_waitcnt lgkmcnt(0)
	v_mul_f32_e32 v67, v48, v67
	v_fmac_f32_e32 v67, v25, v66
	v_fmac_f32_e32 v67, v55, v68
	v_fmac_f32_e32 v67, v56, v69
	v_add_f32_e32 v70, v70, v67
	ds_read_b128 v[66:69], v60 offset:352
	s_waitcnt lgkmcnt(0)
	v_mul_f32_e32 v67, v51, v67
	v_fmac_f32_e32 v67, v50, v66
	v_fmac_f32_e32 v67, v52, v68
	v_fmac_f32_e32 v67, v53, v69
	v_add_f32_e32 v70, v70, v67
	ds_read_b128 v[66:69], v60 offset:368
	s_waitcnt lgkmcnt(0)
	v_mul_f32_e32 v67, v22, v67
	v_fmac_f32_e32 v67, v19, v66
	v_fmac_f32_e32 v67, v24, v68
	v_fmac_f32_e32 v67, v23, v69
	v_add_f32_e32 v66, v70, v67
	v_min_f32_e32 v67, 0, v66
	v_mul_f32_e64 v66, |v66|, s8
	v_exp_f32_e32 v66, v66
	s_nop 0
	v_add_f32_e32 v66, 1.0, v66
	v_cmp_gt_f32_e32 vcc, s89, v66
	s_nop 1
	v_cndmask_b32_e64 v68, 0, 32, vcc
	v_ldexp_f32 v66, v66, v68
	v_log_f32_e32 v66, v66
	s_nop 0
	v_mul_f32_e32 v68, 0x3f317217, v66
	v_fma_f32 v68, v66, s9, -v68
	v_fmac_f32_e32 v68, 0x3377d1cf, v66
	v_fmac_f32_e32 v68, 0x3f317217, v66
	v_cmp_lt_f32_e64 s[0:1], |v66|, s88
	s_nop 1
	v_cndmask_b32_e64 v66, v66, v68, s[0:1]
	v_cndmask_b32_e32 v68, 0, v206, vcc
	v_sub_f32_e32 v66, v66, v68
	ds_read_b128 v[68:71], v60 offset:384
	v_sub_f32_e32 v66, v67, v66
	v_fmamk_f32 v66, v66, 0x3d800000, v65
	s_waitcnt lgkmcnt(0)
	v_mul_f32_e32 v67, v57, v69
	v_fmac_f32_e32 v67, v54, v68
	v_fmac_f32_e32 v67, v58, v70
	v_fmac_f32_e32 v67, v59, v71
	ds_read_b128 v[68:71], v60 offset:400
	v_add_f32_e32 v67, v61, v67
	s_waitcnt lgkmcnt(0)
	v_mul_f32_e32 v69, v48, v69
	v_fmac_f32_e32 v69, v25, v68
	v_fmac_f32_e32 v69, v55, v70
	v_fmac_f32_e32 v69, v56, v71
	v_add_f32_e32 v67, v67, v69
	ds_read_b128 v[68:71], v60 offset:416
	s_waitcnt lgkmcnt(0)
	v_mul_f32_e32 v69, v51, v69
	v_fmac_f32_e32 v69, v50, v68
	v_fmac_f32_e32 v69, v52, v70
	v_fmac_f32_e32 v69, v53, v71
	v_add_f32_e32 v67, v67, v69
	ds_read_b128 v[68:71], v60 offset:432
	s_waitcnt lgkmcnt(0)
	v_mul_f32_e32 v69, v22, v69
	v_fmac_f32_e32 v69, v19, v68
	v_fmac_f32_e32 v69, v24, v70
	v_fmac_f32_e32 v69, v23, v71
	v_add_f32_e32 v67, v67, v69
	v_min_f32_e32 v68, 0, v67
	v_mul_f32_e64 v67, |v67|, s8
	v_exp_f32_e32 v67, v67
	s_nop 0
	v_add_f32_e32 v67, 1.0, v67
	v_cmp_gt_f32_e32 vcc, s89, v67
	s_nop 1
	v_cndmask_b32_e64 v69, 0, 32, vcc
	v_ldexp_f32 v67, v67, v69
	v_log_f32_e32 v67, v67
	s_nop 0
	v_mul_f32_e32 v69, 0x3f317217, v67
	v_fma_f32 v69, v67, s9, -v69
	v_fmac_f32_e32 v69, 0x3377d1cf, v67
	v_fmac_f32_e32 v69, 0x3f317217, v67
	v_cmp_lt_f32_e64 s[0:1], |v67|, s88
	s_nop 1
	v_cndmask_b32_e64 v67, v67, v69, s[0:1]
	v_cndmask_b32_e32 v69, 0, v206, vcc
	v_sub_f32_e32 v67, v67, v69
	v_sub_f32_e32 v67, v68, v67
	ds_read_b128 v[68:71], v60 offset:448
	v_fmamk_f32 v67, v67, 0x3d800000, v66
	s_waitcnt lgkmcnt(0)
	v_mul_f32_e32 v69, v57, v69
	v_fmac_f32_e32 v69, v54, v68
	v_fmac_f32_e32 v69, v58, v70
	v_fmac_f32_e32 v69, v59, v71
	v_add_f32_e32 v72, v61, v69
	ds_read_b128 v[68:71], v60 offset:464
	s_waitcnt lgkmcnt(0)
	v_mul_f32_e32 v69, v48, v69
	v_fmac_f32_e32 v69, v25, v68
	v_fmac_f32_e32 v69, v55, v70
	v_fmac_f32_e32 v69, v56, v71
	v_add_f32_e32 v72, v72, v69
	ds_read_b128 v[68:71], v60 offset:480
	s_waitcnt lgkmcnt(0)
	v_mul_f32_e32 v69, v51, v69
	v_fmac_f32_e32 v69, v50, v68
	v_fmac_f32_e32 v69, v52, v70
	v_fmac_f32_e32 v69, v53, v71
	v_add_f32_e32 v72, v72, v69
	ds_read_b128 v[68:71], v60 offset:496
	s_waitcnt lgkmcnt(0)
	v_mul_f32_e32 v69, v22, v69
	v_fmac_f32_e32 v69, v19, v68
	v_fmac_f32_e32 v69, v24, v70
	v_fmac_f32_e32 v69, v23, v71
	v_add_f32_e32 v68, v72, v69
	v_min_f32_e32 v69, 0, v68
	v_mul_f32_e64 v68, |v68|, s8
	v_exp_f32_e32 v68, v68
	s_nop 0
	v_add_f32_e32 v68, 1.0, v68
	v_cmp_gt_f32_e32 vcc, s89, v68
	s_nop 1
	v_cndmask_b32_e64 v70, 0, 32, vcc
	v_ldexp_f32 v68, v68, v70
	v_log_f32_e32 v68, v68
	s_nop 0
	v_mul_f32_e32 v70, 0x3f317217, v68
	v_fma_f32 v70, v68, s9, -v70
	v_fmac_f32_e32 v70, 0x3377d1cf, v68
	v_fmac_f32_e32 v70, 0x3f317217, v68
	v_cmp_lt_f32_e64 s[0:1], |v68|, s88
	s_nop 1
	v_cndmask_b32_e64 v68, v68, v70, s[0:1]
	v_cndmask_b32_e32 v70, 0, v206, vcc
	v_sub_f32_e32 v68, v68, v70
	ds_read_b128 v[70:73], v60 offset:512
	v_sub_f32_e32 v68, v69, v68
	v_fmamk_f32 v68, v68, 0x3d800000, v67
	s_waitcnt lgkmcnt(0)
; #define LAS __attribute__((address_space(3)))
; __device__ __forceinline__ void gla_gates(const Params& p, int l, int h, int tok0, int d, int tg, LAS float* gsum, float (&b)[16], float& blast) {
;     ...
;     for (int i = 0; i < 16; ++i) {
;         float x = bg;
; #pragma unroll
;         for (int r4 = 0; r4 < 4; ++r4) { const f32x4 a = *(const LAS f32x4*)(lr + i * 16 + r4 * 4);
;             x += a[0] * w[r4 * 4] + a[1] * w[r4 * 4 + 1] + a[2] * w[r4 * 4 + 2] + a[3] * w[r4 * 4 + 3]; }
;         const float ls = fminf(x, 0.f) - __logf(1.f + __expf(-fabsf(x)));
;         run += ls * (1.f / 16.f); b[i] = run;
;     }
	v_mul_f32_e32 v69, v57, v71
	v_fmac_f32_e32 v69, v54, v70
	v_fmac_f32_e32 v69, v58, v72
	v_fmac_f32_e32 v69, v59, v73
	ds_read_b128 v[70:73], v60 offset:528
	v_add_f32_e32 v69, v61, v69
	s_waitcnt lgkmcnt(0)
	v_mul_f32_e32 v71, v48, v71
	v_fmac_f32_e32 v71, v25, v70
	v_fmac_f32_e32 v71, v55, v72
	v_fmac_f32_e32 v71, v56, v73
	v_add_f32_e32 v69, v69, v71
	ds_read_b128 v[70:73], v60 offset:544
	s_waitcnt lgkmcnt(0)
	v_mul_f32_e32 v71, v51, v71
	v_fmac_f32_e32 v71, v50, v70
	v_fmac_f32_e32 v71, v52, v72
	v_fmac_f32_e32 v71, v53, v73
	v_add_f32_e32 v69, v69, v71
	ds_read_b128 v[70:73], v60 offset:560
	s_waitcnt lgkmcnt(0)
	v_mul_f32_e32 v71, v22, v71
	v_fmac_f32_e32 v71, v19, v70
	v_fmac_f32_e32 v71, v24, v72
	v_fmac_f32_e32 v71, v23, v73
	v_add_f32_e32 v69, v69, v71
	v_min_f32_e32 v70, 0, v69
	v_mul_f32_e64 v69, |v69|, s8
	v_exp_f32_e32 v69, v69
	s_nop 0
	v_add_f32_e32 v69, 1.0, v69
	v_cmp_gt_f32_e32 vcc, s89, v69
	s_nop 1
	v_cndmask_b32_e64 v71, 0, 32, vcc
	v_ldexp_f32 v69, v69, v71
	v_log_f32_e32 v69, v69
	s_nop 0
	v_mul_f32_e32 v71, 0x3f317217, v69
	v_fma_f32 v71, v69, s9, -v71
	v_fmac_f32_e32 v71, 0x3377d1cf, v69
	v_fmac_f32_e32 v71, 0x3f317217, v69
	v_cmp_lt_f32_e64 s[0:1], |v69|, s88
	s_nop 1
	v_cndmask_b32_e64 v69, v69, v71, s[0:1]
	v_cndmask_b32_e32 v71, 0, v206, vcc
	v_sub_f32_e32 v69, v69, v71
	v_sub_f32_e32 v69, v70, v69
	ds_read_b128 v[70:73], v60 offset:576
	v_fmamk_f32 v69, v69, 0x3d800000, v68
	s_waitcnt lgkmcnt(0)
	v_mul_f32_e32 v71, v57, v71
	v_fmac_f32_e32 v71, v54, v70
	v_fmac_f32_e32 v71, v58, v72
	v_fmac_f32_e32 v71, v59, v73
	v_add_f32_e32 v74, v61, v71
	ds_read_b128 v[70:73], v60 offset:592
	s_waitcnt lgkmcnt(0)
	v_mul_f32_e32 v71, v48, v71
	v_fmac_f32_e32 v71, v25, v70
	v_fmac_f32_e32 v71, v55, v72
	v_fmac_f32_e32 v71, v56, v73
	v_add_f32_e32 v74, v74, v71
	ds_read_b128 v[70:73], v60 offset:608
	s_waitcnt lgkmcnt(0)
	v_mul_f32_e32 v71, v51, v71
	v_fmac_f32_e32 v71, v50, v70
	v_fmac_f32_e32 v71, v52, v72
	v_fmac_f32_e32 v71, v53, v73
	v_add_f32_e32 v74, v74, v71
	ds_read_b128 v[70:73], v60 offset:624
	s_waitcnt lgkmcnt(0)
	v_mul_f32_e32 v71, v22, v71
	v_fmac_f32_e32 v71, v19, v70
	v_fmac_f32_e32 v71, v24, v72
	v_fmac_f32_e32 v71, v23, v73
	v_add_f32_e32 v70, v74, v71
	v_min_f32_e32 v71, 0, v70
	v_mul_f32_e64 v70, |v70|, s8
	v_exp_f32_e32 v70, v70
	s_nop 0
	v_add_f32_e32 v70, 1.0, v70
	v_cmp_gt_f32_e32 vcc, s89, v70
	s_nop 1
	v_cndmask_b32_e64 v72, 0, 32, vcc
	v_ldexp_f32 v70, v70, v72
	v_log_f32_e32 v70, v70
	s_nop 0
	v_mul_f32_e32 v72, 0x3f317217, v70
	v_fma_f32 v72, v70, s9, -v72
	v_fmac_f32_e32 v72, 0x3377d1cf, v70
	v_fmac_f32_e32 v72, 0x3f317217, v70
	v_cmp_lt_f32_e64 s[0:1], |v70|, s88
	s_nop 1
	v_cndmask_b32_e64 v70, v70, v72, s[0:1]
	v_cndmask_b32_e32 v72, 0, v206, vcc
	v_sub_f32_e32 v70, v70, v72
	ds_read_b128 v[72:75], v60 offset:640
	v_sub_f32_e32 v70, v71, v70
	v_fmamk_f32 v70, v70, 0x3d800000, v69
	s_waitcnt lgkmcnt(0)
	v_mul_f32_e32 v71, v57, v73
	v_fmac_f32_e32 v71, v54, v72
	v_fmac_f32_e32 v71, v58, v74
	v_fmac_f32_e32 v71, v59, v75
	ds_read_b128 v[72:75], v60 offset:656
	v_add_f32_e32 v71, v61, v71
	s_waitcnt lgkmcnt(0)
	v_mul_f32_e32 v73, v48, v73
	v_fmac_f32_e32 v73, v25, v72
	v_fmac_f32_e32 v73, v55, v74
	v_fmac_f32_e32 v73, v56, v75
	v_add_f32_e32 v71, v71, v73
	ds_read_b128 v[72:75], v60 offset:672
	s_waitcnt lgkmcnt(0)
	v_mul_f32_e32 v73, v51, v73
	v_fmac_f32_e32 v73, v50, v72
	v_fmac_f32_e32 v73, v52, v74
	v_fmac_f32_e32 v73, v53, v75
	v_add_f32_e32 v71, v71, v73
	ds_read_b128 v[72:75], v60 offset:688
	s_waitcnt lgkmcnt(0)
	v_mul_f32_e32 v73, v22, v73
	v_fmac_f32_e32 v73, v19, v72
	v_fmac_f32_e32 v73, v24, v74
	v_fmac_f32_e32 v73, v23, v75
	v_add_f32_e32 v71, v71, v73
	v_min_f32_e32 v72, 0, v71
	v_mul_f32_e64 v71, |v71|, s8
	v_exp_f32_e32 v71, v71
	s_nop 0
	v_add_f32_e32 v71, 1.0, v71
	v_cmp_gt_f32_e32 vcc, s89, v71
	s_nop 1
	v_cndmask_b32_e64 v73, 0, 32, vcc
	v_ldexp_f32 v71, v71, v73
	v_log_f32_e32 v71, v71
	s_nop 0
	v_mul_f32_e32 v73, 0x3f317217, v71
	v_fma_f32 v73, v71, s9, -v73
	v_fmac_f32_e32 v73, 0x3377d1cf, v71
	v_fmac_f32_e32 v73, 0x3f317217, v71
	v_cmp_lt_f32_e64 s[0:1], |v71|, s88
	s_nop 1
	v_cndmask_b32_e64 v71, v71, v73, s[0:1]
	v_cndmask_b32_e32 v73, 0, v206, vcc
	v_sub_f32_e32 v71, v71, v73
	v_sub_f32_e32 v71, v72, v71
	ds_read_b128 v[72:75], v60 offset:704
	v_fmamk_f32 v71, v71, 0x3d800000, v70
	s_waitcnt lgkmcnt(0)
	v_mul_f32_e32 v73, v57, v73
	v_fmac_f32_e32 v73, v54, v72
	v_fmac_f32_e32 v73, v58, v74
	v_fmac_f32_e32 v73, v59, v75
	v_add_f32_e32 v76, v61, v73
	ds_read_b128 v[72:75], v60 offset:720
	s_waitcnt lgkmcnt(0)
	v_mul_f32_e32 v73, v48, v73
	v_fmac_f32_e32 v73, v25, v72
	v_fmac_f32_e32 v73, v55, v74
	v_fmac_f32_e32 v73, v56, v75
	v_add_f32_e32 v76, v76, v73
	ds_read_b128 v[72:75], v60 offset:736
	s_waitcnt lgkmcnt(0)
	v_mul_f32_e32 v73, v51, v73
	v_fmac_f32_e32 v73, v50, v72
	v_fmac_f32_e32 v73, v52, v74
	v_fmac_f32_e32 v73, v53, v75
	v_add_f32_e32 v76, v76, v73
	ds_read_b128 v[72:75], v60 offset:752
	s_waitcnt lgkmcnt(0)
	v_mul_f32_e32 v73, v22, v73
	v_fmac_f32_e32 v73, v19, v72
	v_fmac_f32_e32 v73, v24, v74
	v_fmac_f32_e32 v73, v23, v75
	v_add_f32_e32 v72, v76, v73
	v_min_f32_e32 v73, 0, v72
	v_mul_f32_e64 v72, |v72|, s8
	v_exp_f32_e32 v72, v72
	s_nop 0
	v_add_f32_e32 v72, 1.0, v72
	v_cmp_gt_f32_e32 vcc, s89, v72
	s_nop 1
	v_cndmask_b32_e64 v74, 0, 32, vcc
	v_ldexp_f32 v72, v72, v74
	v_log_f32_e32 v72, v72
	s_nop 0
	v_mul_f32_e32 v74, 0x3f317217, v72
	v_fma_f32 v74, v72, s9, -v74
	v_fmac_f32_e32 v74, 0x3377d1cf, v72
	v_fmac_f32_e32 v74, 0x3f317217, v72
	v_cmp_lt_f32_e64 s[0:1], |v72|, s88
	s_nop 1
	v_cndmask_b32_e64 v72, v72, v74, s[0:1]
	v_cndmask_b32_e32 v74, 0, v206, vcc
	v_sub_f32_e32 v72, v72, v74
	ds_read_b128 v[74:77], v60 offset:768
	v_sub_f32_e32 v72, v73, v72
	v_fmamk_f32 v72, v72, 0x3d800000, v71
	s_waitcnt lgkmcnt(0)
; #define LAS __attribute__((address_space(3)))
; __device__ __forceinline__ unsigned cvt_pk_bf16(float lo, float hi) { unsigned r; asm("v_cvt_pk_bf16_f32 %0, %1, %2" : "=v"(r) : "v"(lo), "v"(hi)); return r; }
; __device__ __forceinline__ void gla_gates(const Params& p, int l, int h, int tok0, int d, int tg, LAS float* gsum, float (&b)[16], float& blast) {
;     ...
;     for (int i = 0; i < 16; ++i) {
;         float x = bg;
; #pragma unroll
;         for (int r4 = 0; r4 < 4; ++r4) { const f32x4 a = *(const LAS f32x4*)(lr + i * 16 + r4 * 4);
;             x += a[0] * w[r4 * 4] + a[1] * w[r4 * 4 + 1] + a[2] * w[r4 * 4 + 2] + a[3] * w[r4 * 4 + 3]; }
;         const float ls = fminf(x, 0.f) - __logf(1.f + __expf(-fabsf(x)));
;         run += ls * (1.f / 16.f); b[i] = run;
;     }
;     gsum[tg * 128 + d] = run;
;     __syncthreads();
;     float off = 0.f, tot = 0.f;
; #pragma unroll
;     for (int g = 0; g < 4; ++g) { const float v = gsum[g * 128 + d]; tot += v; if (g < tg) off += v; }
; #pragma unroll
;     for (int i = 0; i < 16; ++i) b[i] += off;
;     blast = tot;
; __device__ __forceinline__ void gla_local_item(const Params& p, int l, int c, int h, LAS unsigned char* lds) {
;     ...
;         for (int i = 0; i < 16; ++i) {
;             const float ev = __expf(b[i]);
;             const float eo = __shfl_down(ev, 1);
;             if ((d & 1) == 0) bc[i * 256] = cvt_pk_bf16(ev, eo);
	v_mul_f32_e32 v73, v57, v75
	v_fmac_f32_e32 v73, v54, v74
	v_fmac_f32_e32 v73, v58, v76
	v_fmac_f32_e32 v73, v59, v77
	ds_read_b128 v[74:77], v60 offset:784
	v_add_f32_e32 v73, v61, v73
	s_waitcnt lgkmcnt(0)
	v_mul_f32_e32 v75, v48, v75
	v_fmac_f32_e32 v75, v25, v74
	v_fmac_f32_e32 v75, v55, v76
	v_fmac_f32_e32 v75, v56, v77
	v_add_f32_e32 v73, v73, v75
	ds_read_b128 v[74:77], v60 offset:800
	s_waitcnt lgkmcnt(0)
	v_mul_f32_e32 v75, v51, v75
	v_fmac_f32_e32 v75, v50, v74
	v_fmac_f32_e32 v75, v52, v76
	v_fmac_f32_e32 v75, v53, v77
	v_add_f32_e32 v73, v73, v75
	ds_read_b128 v[74:77], v60 offset:816
	s_waitcnt lgkmcnt(0)
	v_mul_f32_e32 v75, v22, v75
	v_fmac_f32_e32 v75, v19, v74
	v_fmac_f32_e32 v75, v24, v76
	v_fmac_f32_e32 v75, v23, v77
	v_add_f32_e32 v73, v73, v75
	v_min_f32_e32 v74, 0, v73
	v_mul_f32_e64 v73, |v73|, s8
	v_exp_f32_e32 v73, v73
	s_nop 0
	v_add_f32_e32 v73, 1.0, v73
	v_cmp_gt_f32_e32 vcc, s89, v73
	s_nop 1
	v_cndmask_b32_e64 v75, 0, 32, vcc
	v_ldexp_f32 v73, v73, v75
	v_log_f32_e32 v73, v73
	s_nop 0
	v_mul_f32_e32 v75, 0x3f317217, v73
	v_fma_f32 v75, v73, s9, -v75
	v_fmac_f32_e32 v75, 0x3377d1cf, v73
	v_fmac_f32_e32 v75, 0x3f317217, v73
	v_cmp_lt_f32_e64 s[0:1], |v73|, s88
	s_nop 1
	v_cndmask_b32_e64 v73, v73, v75, s[0:1]
	v_cndmask_b32_e32 v75, 0, v206, vcc
	v_sub_f32_e32 v73, v73, v75
	v_sub_f32_e32 v73, v74, v73
	ds_read_b128 v[74:77], v60 offset:832
	v_fmamk_f32 v73, v73, 0x3d800000, v72
	s_waitcnt lgkmcnt(0)
	v_mul_f32_e32 v75, v57, v75
	v_fmac_f32_e32 v75, v54, v74
	v_fmac_f32_e32 v75, v58, v76
	v_fmac_f32_e32 v75, v59, v77
	v_add_f32_e32 v78, v61, v75
	ds_read_b128 v[74:77], v60 offset:848
	s_waitcnt lgkmcnt(0)
	v_mul_f32_e32 v75, v48, v75
	v_fmac_f32_e32 v75, v25, v74
	v_fmac_f32_e32 v75, v55, v76
	v_fmac_f32_e32 v75, v56, v77
	v_add_f32_e32 v78, v78, v75
	ds_read_b128 v[74:77], v60 offset:864
	s_waitcnt lgkmcnt(0)
	v_mul_f32_e32 v75, v51, v75
	v_fmac_f32_e32 v75, v50, v74
	v_fmac_f32_e32 v75, v52, v76
	v_fmac_f32_e32 v75, v53, v77
	v_add_f32_e32 v78, v78, v75
	ds_read_b128 v[74:77], v60 offset:880
	s_waitcnt lgkmcnt(0)
	v_mul_f32_e32 v75, v22, v75
	v_fmac_f32_e32 v75, v19, v74
	v_fmac_f32_e32 v75, v24, v76
	v_fmac_f32_e32 v75, v23, v77
	v_add_f32_e32 v74, v78, v75
	v_min_f32_e32 v75, 0, v74
	v_mul_f32_e64 v74, |v74|, s8
	v_exp_f32_e32 v74, v74
	s_nop 0
	v_add_f32_e32 v74, 1.0, v74
	v_cmp_gt_f32_e32 vcc, s89, v74
	s_nop 1
	v_cndmask_b32_e64 v76, 0, 32, vcc
	v_ldexp_f32 v74, v74, v76
	v_log_f32_e32 v74, v74
	s_nop 0
	v_mul_f32_e32 v76, 0x3f317217, v74
	v_fma_f32 v76, v74, s9, -v76
	v_fmac_f32_e32 v76, 0x3377d1cf, v74
	v_fmac_f32_e32 v76, 0x3f317217, v74
	v_cmp_lt_f32_e64 s[0:1], |v74|, s88
	s_nop 1
	v_cndmask_b32_e64 v74, v74, v76, s[0:1]
	v_cndmask_b32_e32 v76, 0, v206, vcc
	v_sub_f32_e32 v74, v74, v76
	ds_read_b128 v[76:79], v60 offset:896
	v_sub_f32_e32 v74, v75, v74
	v_fmamk_f32 v74, v74, 0x3d800000, v73
	s_waitcnt lgkmcnt(0)
	v_mul_f32_e32 v75, v57, v77
	v_fmac_f32_e32 v75, v54, v76
	v_fmac_f32_e32 v75, v58, v78
	v_fmac_f32_e32 v75, v59, v79
	ds_read_b128 v[76:79], v60 offset:912
	v_add_f32_e32 v75, v61, v75
	s_waitcnt lgkmcnt(0)
	v_mul_f32_e32 v77, v48, v77
	v_fmac_f32_e32 v77, v25, v76
	v_fmac_f32_e32 v77, v55, v78
	v_fmac_f32_e32 v77, v56, v79
	v_add_f32_e32 v75, v75, v77
	ds_read_b128 v[76:79], v60 offset:928
	s_waitcnt lgkmcnt(0)
	v_mul_f32_e32 v77, v51, v77
	v_fmac_f32_e32 v77, v50, v76
	v_fmac_f32_e32 v77, v52, v78
	v_fmac_f32_e32 v77, v53, v79
	v_add_f32_e32 v75, v75, v77
	ds_read_b128 v[76:79], v60 offset:944
	s_waitcnt lgkmcnt(0)
	v_mul_f32_e32 v77, v22, v77
	v_fmac_f32_e32 v77, v19, v76
	v_fmac_f32_e32 v77, v24, v78
	v_fmac_f32_e32 v77, v23, v79
	v_add_f32_e32 v75, v75, v77
	v_min_f32_e32 v76, 0, v75
	v_mul_f32_e64 v75, |v75|, s8
	v_exp_f32_e32 v75, v75
	s_nop 0
	v_add_f32_e32 v75, 1.0, v75
	v_cmp_gt_f32_e32 vcc, s89, v75
	s_nop 1
	v_cndmask_b32_e64 v77, 0, 32, vcc
	v_ldexp_f32 v75, v75, v77
	v_log_f32_e32 v75, v75
	s_nop 0
	v_mul_f32_e32 v77, 0x3f317217, v75
	v_fma_f32 v77, v75, s9, -v77
	v_fmac_f32_e32 v77, 0x3377d1cf, v75
	v_fmac_f32_e32 v77, 0x3f317217, v75
	v_cmp_lt_f32_e64 s[0:1], |v75|, s88
	s_nop 1
	v_cndmask_b32_e64 v75, v75, v77, s[0:1]
	v_cndmask_b32_e32 v77, 0, v206, vcc
	v_sub_f32_e32 v75, v75, v77
	v_sub_f32_e32 v75, v76, v75
	ds_read_b128 v[76:79], v60 offset:960
	v_fmamk_f32 v75, v75, 0x3d800000, v74
	s_waitcnt lgkmcnt(0)
	v_mul_f32_e32 v57, v57, v77
	v_fmac_f32_e32 v57, v54, v76
	v_fmac_f32_e32 v57, v58, v78
	v_fmac_f32_e32 v57, v59, v79
	ds_read_b128 v[76:79], v60 offset:976
	v_add_f32_e32 v54, v61, v57
	s_waitcnt lgkmcnt(0)
	v_mul_f32_e32 v48, v48, v77
	v_fmac_f32_e32 v48, v25, v76
	v_fmac_f32_e32 v48, v55, v78
	v_fmac_f32_e32 v48, v56, v79
	v_add_f32_e32 v25, v54, v48
	ds_read_b128 v[54:57], v60 offset:992
	s_waitcnt lgkmcnt(0)
	v_mul_f32_e32 v48, v51, v55
	v_fmac_f32_e32 v48, v50, v54
	v_fmac_f32_e32 v48, v52, v56
	v_fmac_f32_e32 v48, v53, v57
	ds_read_b128 v[50:53], v60 offset:1008
	v_add_f32_e32 v25, v25, v48
	s_waitcnt lgkmcnt(0)
	v_mul_f32_e32 v22, v22, v51
	v_fmac_f32_e32 v22, v19, v50
	v_fmac_f32_e32 v22, v24, v52
	v_fmac_f32_e32 v22, v23, v53
	v_add_f32_e32 v19, v25, v22
	v_min_f32_e32 v22, 0, v19
	v_mul_f32_e64 v19, |v19|, s8
	v_exp_f32_e32 v19, v19
	v_mov_b32_e32 v53, v1
	v_add_f32_e32 v19, 1.0, v19
	v_cmp_gt_f32_e32 vcc, s89, v19
	s_nop 1
	v_cndmask_b32_e64 v23, 0, 32, vcc
	v_ldexp_f32 v19, v19, v23
	v_log_f32_e32 v19, v19
	s_nop 0
	v_mul_f32_e32 v23, 0x3f317217, v19
	v_fma_f32 v23, v19, s9, -v23
	v_fmac_f32_e32 v23, 0x3377d1cf, v19
	v_fmac_f32_e32 v23, 0x3f317217, v19
	v_cmp_lt_f32_e64 s[0:1], |v19|, s88
	s_nop 1
	v_cndmask_b32_e64 v19, v19, v23, s[0:1]
	v_cndmask_b32_e32 v23, 0, v206, vcc
	v_sub_f32_e32 v19, v19, v23
	v_sub_f32_e32 v19, v22, v19
	v_fmamk_f32 v48, v19, 0x3d800000, v75
	v_add_u32_e32 v19, 0, v18
	v_lshl_add_u32 v22, v31, 9, v19
	ds_write_b32 v22, v48
	s_waitcnt lgkmcnt(0)
	s_barrier
	ds_read2st64_b32 v[22:23], v19 offset1:2
	v_cmp_lt_i32_e32 vcc, 0, v31
	s_waitcnt lgkmcnt(0)
	v_add_f32_e32 v22, 0, v22
	v_cndmask_b32_e32 v24, 0, v22, vcc
	v_cmp_lt_i32_e32 vcc, 1, v31
	v_add_f32_e32 v25, v23, v24
	s_nop 0
	v_cndmask_b32_e32 v50, v24, v25, vcc
	ds_read2st64_b32 v[24:25], v19 offset0:4 offset1:6
	v_cmp_lt_i32_e32 vcc, 2, v31
	s_waitcnt lgkmcnt(0)
	v_add_f32_e32 v51, v24, v50
	v_cndmask_b32_e32 v50, v50, v51, vcc
	v_cmp_lt_i32_e32 vcc, 3, v31
	v_add_f32_e32 v51, v25, v50
	s_nop 0
	v_cndmask_b32_e32 v50, v50, v51, vcc
	v_and_b32_e32 v51, 0x7e, v30
	v_lshlrev_b32_e32 v52, 1, v51
	v_add_f32_e32 v49, v49, v50
	v_lshl_add_u64 v[20:21], v[20:21], 0, v[52:53]
	v_and_b32_e32 v52, 1, v30
	v_cmp_eq_u32_e64 s[38:39], 0, v52
	v_mul_f32_e32 v52, 0x3fb8aa3b, v49
	v_and_b32_e32 v51, 63, v205
	v_exp_f32_e32 v52, v52
	v_cmp_ne_u32_e32 vcc, 63, v51
	s_nop 1
	v_addc_co_u32_e32 v51, vcc, 0, v205, vcc
	v_lshlrev_b32_e32 v51, 2, v51
	ds_bpermute_b32 v53, v51, v52
	s_and_saveexec_b64 s[0:1], s[38:39]
	s_cbranch_execz .LBB0_507
	s_waitcnt lgkmcnt(0)
	v_cvt_pk_bf16_f32 v52, v52, v53
	global_store_dword v[20:21], v52, off
